# cbias GEMV inner loop: 32 weight-row loads in flight per trip instead of 16 (same accumulation order)
# speedup vs baseline: 1.0502x; 1.0006x over previous
.LBB0_83:
	v_add_u32_e32 v13, 32, v13
	v_add_co_u32_e32 v14, vcc, 0xffffd000, v6
	s_nop 1
	v_addc_co_u32_e32 v15, vcc, -1, v7, vcc
	global_load_dword v42, v[14:15], off offset:-3072
	global_load_dword v43, v[14:15], off offset:-2048
	global_load_dword v44, v[14:15], off offset:-1024
	global_load_dword v45, v[14:15], off
	v_add_co_u32_e32 v14, vcc, 0xffffe000, v6
	s_nop 1
	v_addc_co_u32_e32 v15, vcc, -1, v7, vcc
	global_load_dword v30, v[14:15], off offset:-3072
	global_load_dword v31, v[14:15], off offset:-2048
	global_load_dword v32, v[14:15], off offset:-1024
	global_load_dword v33, v[14:15], off
	v_add_co_u32_e32 v14, vcc, 0xfffff000, v6
	s_nop 1
	v_addc_co_u32_e32 v15, vcc, -1, v7, vcc
	global_load_dword v34, v[14:15], off offset:-3072
	global_load_dword v35, v[14:15], off offset:-2048
	global_load_dword v36, v[14:15], off offset:-1024
	global_load_dword v37, v[6:7], off offset:-4096
	global_load_dword v38, v[6:7], off offset:-3072
	global_load_dword v39, v[6:7], off offset:-2048
	global_load_dword v40, v[6:7], off offset:-1024
	global_load_dword v41, v[6:7], off
	v_lshl_add_u64 v[78:79], v[6:7], 0, s[24:25]
	v_add_co_u32_e32 v14, vcc, 0xffffd000, v78
	s_nop 1
	v_addc_co_u32_e32 v15, vcc, -1, v79, vcc
	global_load_dword v46, v[14:15], off offset:-3072
	global_load_dword v47, v[14:15], off offset:-2048
	global_load_dword v48, v[14:15], off offset:-1024
	global_load_dword v49, v[14:15], off
	v_add_co_u32_e32 v14, vcc, 0xffffe000, v78
	s_nop 1
	v_addc_co_u32_e32 v15, vcc, -1, v79, vcc
	global_load_dword v50, v[14:15], off offset:-3072
	global_load_dword v51, v[14:15], off offset:-2048
	global_load_dword v52, v[14:15], off offset:-1024
	global_load_dword v53, v[14:15], off
	v_add_co_u32_e32 v14, vcc, 0xfffff000, v78
	s_nop 1
	v_addc_co_u32_e32 v15, vcc, -1, v79, vcc
	global_load_dword v54, v[14:15], off offset:-3072
	global_load_dword v55, v[14:15], off offset:-2048
	global_load_dword v56, v[14:15], off offset:-1024
	global_load_dword v57, v[78:79], off offset:-4096
	global_load_dword v58, v[78:79], off offset:-3072
	global_load_dword v59, v[78:79], off offset:-2048
	global_load_dword v60, v[78:79], off offset:-1024
	global_load_dword v61, v[78:79], off
	ds_read_b128 v[14:17], v1
	ds_read_b128 v[18:21], v1 offset:16
	ds_read_b128 v[22:25], v1 offset:32
	ds_read_b128 v[26:29], v1 offset:48
	ds_read_b128 v[62:65], v1 offset:64
	ds_read_b128 v[66:69], v1 offset:80
	ds_read_b128 v[70:73], v1 offset:96
	ds_read_b128 v[74:77], v1 offset:112
	v_cmp_ge_i32_e32 vcc, v13, v8
	v_add_u32_e32 v1, 0x80, v1
	v_lshl_add_u64 v[6:7], v[6:7], 0, s[24:25]
	v_lshl_add_u64 v[6:7], v[6:7], 0, s[24:25]
	s_or_b64 s[18:19], vcc, s[18:19]
	s_waitcnt vmcnt(31) lgkmcnt(7)
	v_fmac_f32_e32 v12, v42, v14
	s_waitcnt vmcnt(30)
	v_fmac_f32_e32 v12, v43, v15
	s_waitcnt vmcnt(29)
	v_fmac_f32_e32 v12, v44, v16
	s_waitcnt vmcnt(28)
	v_fmac_f32_e32 v12, v45, v17
	s_waitcnt vmcnt(26) lgkmcnt(6)
	v_pk_mul_f32 v[14:15], v[30:31], v[18:19]
	s_nop 0
	v_add_f32_e32 v12, v12, v14
	v_add_f32_e32 v12, v12, v15
	s_waitcnt vmcnt(24)
	v_pk_mul_f32 v[14:15], v[32:33], v[20:21]
	s_nop 0
	v_add_f32_e32 v12, v12, v14
	v_add_f32_e32 v12, v12, v15
	s_waitcnt vmcnt(22) lgkmcnt(5)
	v_pk_mul_f32 v[14:15], v[34:35], v[22:23]
	s_nop 0
	v_add_f32_e32 v12, v12, v14
	v_add_f32_e32 v12, v12, v15
	s_waitcnt vmcnt(20)
	v_pk_mul_f32 v[14:15], v[36:37], v[24:25]
	s_nop 0
	v_add_f32_e32 v12, v12, v14
	v_add_f32_e32 v12, v12, v15
	s_waitcnt vmcnt(18) lgkmcnt(4)
	v_pk_mul_f32 v[14:15], v[38:39], v[26:27]
	s_nop 0
	v_add_f32_e32 v12, v12, v14
	v_add_f32_e32 v12, v12, v15
	s_waitcnt vmcnt(16)
	v_pk_mul_f32 v[14:15], v[40:41], v[28:29]
	s_nop 0
	v_add_f32_e32 v12, v12, v14
	v_add_f32_e32 v12, v12, v15
	s_waitcnt vmcnt(15) lgkmcnt(3)
	v_fmac_f32_e32 v12, v46, v62
	s_waitcnt vmcnt(14)
	v_fmac_f32_e32 v12, v47, v63
	s_waitcnt vmcnt(13)
	v_fmac_f32_e32 v12, v48, v64
	s_waitcnt vmcnt(12)
	v_fmac_f32_e32 v12, v49, v65
	s_waitcnt vmcnt(10) lgkmcnt(2)
	v_pk_mul_f32 v[14:15], v[50:51], v[66:67]
	s_nop 0
	v_add_f32_e32 v12, v12, v14
	v_add_f32_e32 v12, v12, v15
	s_waitcnt vmcnt(8)
	v_pk_mul_f32 v[14:15], v[52:53], v[68:69]
	s_nop 0
	v_add_f32_e32 v12, v12, v14
	v_add_f32_e32 v12, v12, v15
	s_waitcnt vmcnt(6) lgkmcnt(1)
	v_pk_mul_f32 v[14:15], v[54:55], v[70:71]
	s_nop 0
	v_add_f32_e32 v12, v12, v14
	v_add_f32_e32 v12, v12, v15
	s_waitcnt vmcnt(4)
	v_pk_mul_f32 v[14:15], v[56:57], v[72:73]
	s_nop 0
	v_add_f32_e32 v12, v12, v14
	v_add_f32_e32 v12, v12, v15
	s_waitcnt vmcnt(2) lgkmcnt(0)
	v_pk_mul_f32 v[14:15], v[58:59], v[74:75]
	s_nop 0
	v_add_f32_e32 v12, v12, v14
	v_add_f32_e32 v12, v12, v15
	s_waitcnt vmcnt(0)
	v_pk_mul_f32 v[14:15], v[60:61], v[76:77]
	s_nop 0
	v_add_f32_e32 v12, v12, v14
	v_add_f32_e32 v12, v12, v15
	s_andn2_b64 exec, exec, s[18:19]
	s_cbranch_execnz .LBB0_83
	s_or_b64 exec, exec, s[18:19]
